# v80 + accumulator clears in the six GEMM tile prologues done with 64-bit moves (63 v_mov_b64 instead of 126 v_mov_b32 per tile)
# speedup vs baseline: 1.0050x; 1.0050x over previous
; template <class Epi, class Sched, bool ALIGN_EPI = false, bool SP2 = false>
; __device__ __forceinline__ void gemm_phase(PG8_LAS unsigned char* lds, const Gemm g, const Sched& S, const Epi& E) {
;     ...
;         const bool has_next = S.next(ui + 1, nxt);
;         const char* nA = has_next ? (const char*)g.A + (size_t)nxt.pm * tstep : cA; const char* nB = has_next ? (const char*)g.Bt + (size_t)nxt.pn * tstep : cB;
;         for (int t = 0; t < nt; t += 2) {
;             const bool last = (t == nt - 2);
;             const char* a1 = cA + (size_t)(t + 1) * kstep;
;             const char* a2 = last ? nA : cA + (size_t)(t + 2) * kstep; const char* b2 = last ? nB : cB + (size_t)(t + 2) * kstep;
;             const char* a3 = a2 + kstep; const char* b3 = b2 + kstep;
;     ...
; #pragma unroll
;         for (int a = 0; a < 2; ++a)
; #pragma unroll
;             for (int b = 0; b < 2; ++b)
; #pragma unroll
;                 for (int m = 0; m < 4; ++m)
; #pragma unroll
;                     for (int n = 0; n < 2; ++n) acc[a][b][m][n] = (f32x4){0.f, 0.f, 0.f, 0.f};
;         cur = nxt; cA = nA; cB = nB; ++ui;
.LBB0_85:
	s_ashr_i32 s29, s28, 31
	s_lshl_b64 s[26:27], s[28:29], 20
	s_add_u32 s30, s22, s26
	s_addc_u32 s31, s23, s27
	s_and_b64 s[26:27], s[36:37], exec
	s_cselect_b32 s29, s31, s41
	s_cselect_b32 s50, s30, s40
	s_ashr_i32 s19, s18, 31
	s_lshl_b64 s[26:27], s[18:19], 20
	v_readlane_b32 s34, v254, 40
	v_readlane_b32 s35, v254, 41
	s_add_u32 s34, s34, s26
	s_addc_u32 s35, s35, s27
	s_and_b64 s[26:27], s[36:37], exec
	s_cselect_b32 s19, s35, s39
	s_cselect_b32 s51, s34, s38
	s_add_u32 s52, s38, 0x100
	s_addc_u32 s53, s39, 0
	s_add_u32 s38, s40, 0x80080
	v_mov_b32_e32 v4, 0
	s_addc_u32 s39, s41, 0
	s_mov_b32 s54, -2
	v_mov_b32_e32 v5, v4
	v_mov_b64_e32 v[6:7], 0
	v_mov_b64_e32 v[8:9], 0
	v_mov_b64_e32 v[10:11], 0
	v_mov_b64_e32 v[16:17], 0
	v_mov_b64_e32 v[18:19], 0
	v_mov_b64_e32 v[24:25], 0
	v_mov_b64_e32 v[26:27], 0
	s_waitcnt vmcnt(0)
	v_mov_b64_e32 v[32:33], 0
	v_mov_b64_e32 v[34:35], 0
	v_mov_b64_e32 v[40:41], 0
	v_mov_b64_e32 v[42:43], 0
	v_mov_b64_e32 v[48:49], 0
	v_mov_b64_e32 v[50:51], 0
	v_mov_b64_e32 v[56:57], 0
	v_mov_b64_e32 v[58:59], 0
	v_mov_b64_e32 v[12:13], 0
	v_mov_b64_e32 v[14:15], 0
	v_mov_b64_e32 v[20:21], 0
	v_mov_b64_e32 v[22:23], 0
	v_mov_b64_e32 v[28:29], 0
	v_mov_b64_e32 v[30:31], 0
	v_mov_b64_e32 v[36:37], 0
	v_mov_b64_e32 v[38:39], 0
	v_mov_b64_e32 v[44:45], 0
	v_mov_b64_e32 v[46:47], 0
	v_mov_b64_e32 v[52:53], 0
	v_mov_b64_e32 v[54:55], 0
	v_mov_b64_e32 v[60:61], 0
	v_mov_b64_e32 v[62:63], 0
	v_mov_b64_e32 v[64:65], 0
	v_mov_b64_e32 v[66:67], 0
	v_mov_b64_e32 v[68:69], 0
	v_mov_b64_e32 v[70:71], 0
	v_mov_b64_e32 v[72:73], 0
	v_mov_b64_e32 v[74:75], 0
	v_mov_b64_e32 v[84:85], 0
	v_mov_b64_e32 v[86:87], 0
	v_mov_b64_e32 v[88:89], 0
	v_mov_b64_e32 v[90:91], 0
	v_mov_b64_e32 v[100:101], 0
	v_mov_b64_e32 v[102:103], 0
	v_mov_b64_e32 v[104:105], 0
	v_mov_b64_e32 v[106:107], 0
	v_mov_b64_e32 v[116:117], 0
	v_mov_b64_e32 v[118:119], 0
	v_mov_b64_e32 v[120:121], 0
	v_mov_b64_e32 v[122:123], 0
	v_mov_b64_e32 v[76:77], 0
	v_mov_b64_e32 v[78:79], 0
	v_mov_b64_e32 v[80:81], 0
	v_mov_b64_e32 v[82:83], 0
	v_mov_b64_e32 v[92:93], 0
	v_mov_b64_e32 v[94:95], 0
	v_mov_b64_e32 v[96:97], 0
	v_mov_b64_e32 v[98:99], 0
	v_mov_b64_e32 v[108:109], 0
	v_mov_b64_e32 v[110:111], 0
	v_mov_b64_e32 v[112:113], 0
	v_mov_b64_e32 v[114:115], 0
	v_mov_b64_e32 v[124:125], 0
	v_mov_b64_e32 v[126:127], 0
	v_mov_b64_e32 v[128:129], 0
	v_mov_b64_e32 v[130:131], 0
	v_readfirstlane_b32 s101, v172
	s_nop 3
	s_cmp_ge_u32 s101, 0x100
	s_cbranch_scc1 .Lprio_hi_86
	s_setprio 1
	s_branch .Lprio_done_86

; template <class Epi, class Sched, bool ALIGN_EPI = false, bool SP2 = false>
; __device__ __forceinline__ void gemm_phase(PG8_LAS unsigned char* lds, const Gemm g, const Sched& S, const Epi& E) {
;     ...
;         const bool has_next = S.next(ui + 1, nxt);
;         const char* nA = has_next ? (const char*)g.A + (size_t)nxt.pm * tstep : cA; const char* nB = has_next ? (const char*)g.Bt + (size_t)nxt.pn * tstep : cB;
;         for (int t = 0; t < nt; t += 2) {
;             const bool last = (t == nt - 2);
;             const char* a1 = cA + (size_t)(t + 1) * kstep;
;             const char* a2 = last ? nA : cA + (size_t)(t + 2) * kstep; const char* b2 = last ? nB : cB + (size_t)(t + 2) * kstep;
;             const char* a3 = a2 + kstep; const char* b3 = b2 + kstep;
;     ...
; #pragma unroll
;         for (int a = 0; a < 2; ++a)
; #pragma unroll
;             for (int b = 0; b < 2; ++b)
; #pragma unroll
;                 for (int m = 0; m < 4; ++m)
; #pragma unroll
;                     for (int n = 0; n < 2; ++n) acc[a][b][m][n] = (f32x4){0.f, 0.f, 0.f, 0.f};
;         cur = nxt; cA = nA; cB = nB; ++ui;
.LBB0_406:
	s_ashr_i32 s51, s50, 31
	s_lshl_b64 s[16:17], s[50:51], 20
	s_add_u32 s52, s19, s16
	s_addc_u32 s53, s20, s17
	s_and_b64 s[16:17], s[40:41], exec
	s_cselect_b32 s23, s53, s15
	s_cselect_b32 s24, s52, s14
	s_ashr_i32 s49, s48, 31
	s_lshl_b64 s[16:17], s[48:49], 20
	s_add_u32 s54, s26, s16
	s_addc_u32 s55, s27, s17
	s_and_b64 s[16:17], s[40:41], exec
	s_cselect_b32 s25, s55, s1
	s_cselect_b32 s49, s54, s0
	s_add_u32 s51, s0, 0x100
	s_addc_u32 s57, s1, 0
	s_add_u32 s0, s14, 0x80080
	v_mov_b32_e32 v4, 0
	s_addc_u32 s1, s15, 0
	s_mov_b32 s58, -2
	v_mov_b32_e32 v5, v4
	v_mov_b64_e32 v[6:7], 0
	v_mov_b64_e32 v[8:9], 0
	v_mov_b64_e32 v[10:11], 0
	v_mov_b64_e32 v[12:13], 0
	v_mov_b64_e32 v[14:15], 0
	v_mov_b64_e32 v[16:17], 0
	v_mov_b64_e32 v[18:19], 0
	v_mov_b64_e32 v[20:21], 0
	v_mov_b64_e32 v[22:23], 0
	v_mov_b64_e32 v[24:25], 0
	v_mov_b64_e32 v[26:27], 0
	s_waitcnt vmcnt(0)
	v_mov_b64_e32 v[28:29], 0
	v_mov_b64_e32 v[30:31], 0
	v_mov_b64_e32 v[32:33], 0
	v_mov_b64_e32 v[34:35], 0
	v_mov_b64_e32 v[68:69], 0
	v_mov_b64_e32 v[70:71], 0
	v_mov_b64_e32 v[72:73], 0
	v_mov_b64_e32 v[74:75], 0
	v_mov_b64_e32 v[76:77], 0
	v_mov_b64_e32 v[78:79], 0
	v_mov_b64_e32 v[80:81], 0
	v_mov_b64_e32 v[82:83], 0
	v_mov_b64_e32 v[84:85], 0
	v_mov_b64_e32 v[86:87], 0
	v_mov_b64_e32 v[88:89], 0
	v_mov_b64_e32 v[90:91], 0
	v_mov_b64_e32 v[92:93], 0
	v_mov_b64_e32 v[94:95], 0
	v_mov_b64_e32 v[96:97], 0
	v_mov_b64_e32 v[98:99], 0
	v_mov_b64_e32 v[36:37], 0
	v_mov_b64_e32 v[38:39], 0
	v_mov_b64_e32 v[40:41], 0
	v_mov_b64_e32 v[42:43], 0
	v_mov_b64_e32 v[44:45], 0
	v_mov_b64_e32 v[46:47], 0
	v_mov_b64_e32 v[48:49], 0
	v_mov_b64_e32 v[50:51], 0
	v_mov_b64_e32 v[52:53], 0
	v_mov_b64_e32 v[54:55], 0
	v_mov_b64_e32 v[56:57], 0
	v_mov_b64_e32 v[58:59], 0
	v_mov_b64_e32 v[60:61], 0
	v_mov_b64_e32 v[62:63], 0
	v_mov_b64_e32 v[64:65], 0
	v_mov_b64_e32 v[66:67], 0
	v_mov_b64_e32 v[108:109], 0
	v_mov_b64_e32 v[110:111], 0
	v_mov_b64_e32 v[112:113], 0
	v_mov_b64_e32 v[114:115], 0
	v_mov_b64_e32 v[116:117], 0
	v_mov_b64_e32 v[118:119], 0
	v_mov_b64_e32 v[120:121], 0
	v_mov_b64_e32 v[122:123], 0
	v_mov_b64_e32 v[124:125], 0
	v_mov_b64_e32 v[126:127], 0
	v_mov_b64_e32 v[128:129], 0
	v_mov_b64_e32 v[130:131], 0
	v_mov_b64_e32 v[132:133], 0
	v_mov_b64_e32 v[134:135], 0
	v_mov_b64_e32 v[136:137], 0
	v_mov_b64_e32 v[138:139], 0
	v_readfirstlane_b32 s101, v172
	s_nop 3
	s_cmp_ge_u32 s101, 0x100
	s_cbranch_scc1 .Lprio_hi_407
	s_setprio 1
	s_branch .Lprio_done_407

; template <class Epi, class Sched, bool ALIGN_EPI = false, bool SP2 = false>
; __device__ __forceinline__ void gemm_phase(PG8_LAS unsigned char* lds, const Gemm g, const Sched& S, const Epi& E) {
;     ...
;         const bool has_next = S.next(ui + 1, nxt);
;         const char* nA = has_next ? (const char*)g.A + (size_t)nxt.pm * tstep : cA; const char* nB = has_next ? (const char*)g.Bt + (size_t)nxt.pn * tstep : cB;
;         for (int t = 0; t < nt; t += 2) {
;             const bool last = (t == nt - 2);
;             const char* a1 = cA + (size_t)(t + 1) * kstep;
;             const char* a2 = last ? nA : cA + (size_t)(t + 2) * kstep; const char* b2 = last ? nB : cB + (size_t)(t + 2) * kstep;
;             const char* a3 = a2 + kstep; const char* b3 = b2 + kstep;
;     ...
; #pragma unroll
;         for (int a = 0; a < 2; ++a)
; #pragma unroll
;             for (int b = 0; b < 2; ++b)
; #pragma unroll
;                 for (int m = 0; m < 4; ++m)
; #pragma unroll
;                     for (int n = 0; n < 2; ++n) acc[a][b][m][n] = (f32x4){0.f, 0.f, 0.f, 0.f};
;         cur = nxt; cA = nA; cB = nB; ++ui;
.LBB0_484:
	s_ashr_i32 s53, s52, 31
	s_lshl_b64 s[16:17], s[52:53], 21
	s_add_u32 s54, s19, s16
	s_addc_u32 s55, s20, s17
	s_and_b64 s[16:17], s[40:41], exec
	s_cselect_b32 s23, s55, s15
	s_cselect_b32 s24, s54, s14
	s_ashr_i32 s51, s50, 31
	s_lshl_b64 s[16:17], s[50:51], 21
	s_add_u32 s56, s26, s16
	s_addc_u32 s57, s27, s17
	s_and_b64 s[16:17], s[40:41], exec
	s_cselect_b32 s25, s57, s1
	s_cselect_b32 s51, s56, s0
	s_add_u32 s53, s0, 0x100
	s_addc_u32 s59, s1, 0
	s_add_u32 s0, s14, 0x100080
	v_mov_b32_e32 v4, 0
	s_addc_u32 s1, s15, 0
	s_mov_b32 s60, -2
	v_mov_b32_e32 v5, v4
	v_mov_b64_e32 v[6:7], 0
	v_mov_b64_e32 v[8:9], 0
	v_mov_b64_e32 v[10:11], 0
	v_mov_b64_e32 v[12:13], 0
	v_mov_b64_e32 v[14:15], 0
	v_mov_b64_e32 v[16:17], 0
	v_mov_b64_e32 v[18:19], 0
	v_mov_b64_e32 v[20:21], 0
	v_mov_b64_e32 v[22:23], 0
	v_mov_b64_e32 v[24:25], 0
	v_mov_b64_e32 v[26:27], 0
	s_waitcnt vmcnt(0)
	v_mov_b64_e32 v[28:29], 0
	v_mov_b64_e32 v[30:31], 0
	v_mov_b64_e32 v[32:33], 0
	v_mov_b64_e32 v[34:35], 0
	v_mov_b64_e32 v[68:69], 0
	v_mov_b64_e32 v[70:71], 0
	v_mov_b64_e32 v[72:73], 0
	v_mov_b64_e32 v[74:75], 0
	v_mov_b64_e32 v[76:77], 0
	v_mov_b64_e32 v[78:79], 0
	v_mov_b64_e32 v[80:81], 0
	v_mov_b64_e32 v[82:83], 0
	v_mov_b64_e32 v[84:85], 0
	v_mov_b64_e32 v[86:87], 0
	v_mov_b64_e32 v[88:89], 0
	v_mov_b64_e32 v[90:91], 0
	v_mov_b64_e32 v[92:93], 0
	v_mov_b64_e32 v[94:95], 0
	v_mov_b64_e32 v[96:97], 0
	v_mov_b64_e32 v[98:99], 0
	v_mov_b64_e32 v[36:37], 0
	v_mov_b64_e32 v[38:39], 0
	v_mov_b64_e32 v[40:41], 0
	v_mov_b64_e32 v[42:43], 0
	v_mov_b64_e32 v[44:45], 0
	v_mov_b64_e32 v[46:47], 0
	v_mov_b64_e32 v[48:49], 0
	v_mov_b64_e32 v[50:51], 0
	v_mov_b64_e32 v[52:53], 0
	v_mov_b64_e32 v[54:55], 0
	v_mov_b64_e32 v[56:57], 0
	v_mov_b64_e32 v[58:59], 0
	v_mov_b64_e32 v[60:61], 0
	v_mov_b64_e32 v[62:63], 0
	v_mov_b64_e32 v[64:65], 0
	v_mov_b64_e32 v[66:67], 0
	v_mov_b64_e32 v[108:109], 0
	v_mov_b64_e32 v[110:111], 0
	v_mov_b64_e32 v[112:113], 0
	v_mov_b64_e32 v[114:115], 0
	v_mov_b64_e32 v[116:117], 0
	v_mov_b64_e32 v[118:119], 0
	v_mov_b64_e32 v[120:121], 0
	v_mov_b64_e32 v[122:123], 0
	v_mov_b64_e32 v[124:125], 0
	v_mov_b64_e32 v[126:127], 0
	v_mov_b64_e32 v[128:129], 0
	v_mov_b64_e32 v[130:131], 0
	v_mov_b64_e32 v[132:133], 0
	v_mov_b64_e32 v[134:135], 0
	v_mov_b64_e32 v[136:137], 0
	v_mov_b64_e32 v[138:139], 0
	v_readfirstlane_b32 s101, v172
	s_nop 3
	s_cmp_ge_u32 s101, 0x100
	s_cbranch_scc1 .Lprio_hi_485
	s_setprio 1
	s_branch .Lprio_done_485

; template <class Epi, class Sched, bool ALIGN_EPI = false, bool SP2 = false>
; __device__ __forceinline__ void gemm_phase(PG8_LAS unsigned char* lds, const Gemm g, const Sched& S, const Epi& E) {
;     ...
;         const bool has_next = S.next(ui + 1, nxt);
;         const char* nA = has_next ? (const char*)g.A + (size_t)nxt.pm * tstep : cA; const char* nB = has_next ? (const char*)g.Bt + (size_t)nxt.pn * tstep : cB;
;         for (int t = 0; t < nt; t += 2) {
;             const bool last = (t == nt - 2);
;             const char* a1 = cA + (size_t)(t + 1) * kstep;
;             const char* a2 = last ? nA : cA + (size_t)(t + 2) * kstep; const char* b2 = last ? nB : cB + (size_t)(t + 2) * kstep;
;             const char* a3 = a2 + kstep; const char* b3 = b2 + kstep;
;     ...
; #pragma unroll
;         for (int a = 0; a < 2; ++a)
; #pragma unroll
;             for (int b = 0; b < 2; ++b)
; #pragma unroll
;                 for (int m = 0; m < 4; ++m)
; #pragma unroll
;                     for (int n = 0; n < 2; ++n) acc[a][b][m][n] = (f32x4){0.f, 0.f, 0.f, 0.f};
;         cur = nxt; cA = nA; cB = nB; ++ui;
.LBB0_562:
	s_ashr_i32 s39, s38, 31
	s_lshl_b64 s[26:27], s[38:39], 20
	s_add_u32 s44, s22, s26
	s_addc_u32 s45, s23, s27
	s_and_b64 s[26:27], s[42:43], exec
	s_cselect_b32 s39, s45, s19
	s_cselect_b32 s59, s44, s18
	s_ashr_i32 s37, s36, 31
	s_lshl_b64 s[26:27], s[36:37], 20
	s_add_u32 s46, s24, s26
	s_addc_u32 s47, s25, s27
	s_and_b64 s[26:27], s[42:43], exec
	s_cselect_b32 s37, s47, s1
	s_cselect_b32 s60, s46, s0
	s_add_u32 s61, s0, 0x100
	s_addc_u32 s62, s1, 0
	s_add_u32 s0, s18, 0x80080
	v_mov_b32_e32 v4, 0
	s_addc_u32 s1, s19, 0
	s_mov_b32 s63, -2
	s_waitcnt lgkmcnt(0)
	v_mov_b32_e32 v5, v4
	v_mov_b64_e32 v[6:7], 0
	v_mov_b64_e32 v[8:9], 0
	v_mov_b64_e32 v[10:11], 0
	v_mov_b64_e32 v[20:21], 0
	v_mov_b64_e32 v[22:23], 0
	v_mov_b64_e32 v[24:25], 0
	v_mov_b64_e32 v[26:27], 0
	s_waitcnt vmcnt(0)
	v_mov_b64_e32 v[36:37], 0
	v_mov_b64_e32 v[38:39], 0
	v_mov_b64_e32 v[40:41], 0
	v_mov_b64_e32 v[42:43], 0
	v_mov_b64_e32 v[52:53], 0
	v_mov_b64_e32 v[54:55], 0
	v_mov_b64_e32 v[56:57], 0
	v_mov_b64_e32 v[58:59], 0
	v_mov_b64_e32 v[12:13], 0
	v_mov_b64_e32 v[14:15], 0
	v_mov_b64_e32 v[16:17], 0
	v_mov_b64_e32 v[18:19], 0
	v_mov_b64_e32 v[28:29], 0
	v_mov_b64_e32 v[30:31], 0
	v_mov_b64_e32 v[32:33], 0
	v_mov_b64_e32 v[34:35], 0
	v_mov_b64_e32 v[44:45], 0
	v_mov_b64_e32 v[46:47], 0
	v_mov_b64_e32 v[48:49], 0
	v_mov_b64_e32 v[50:51], 0
	v_mov_b64_e32 v[60:61], 0
	v_mov_b64_e32 v[62:63], 0
	v_mov_b64_e32 v[64:65], 0
	v_mov_b64_e32 v[66:67], 0
	v_mov_b64_e32 v[68:69], 0
	v_mov_b64_e32 v[70:71], 0
	v_mov_b64_e32 v[72:73], 0
	v_mov_b64_e32 v[74:75], 0
	v_mov_b64_e32 v[84:85], 0
	v_mov_b64_e32 v[86:87], 0
	v_mov_b64_e32 v[88:89], 0
	v_mov_b64_e32 v[90:91], 0
	v_mov_b64_e32 v[100:101], 0
	v_mov_b64_e32 v[102:103], 0
	v_mov_b64_e32 v[104:105], 0
	v_mov_b64_e32 v[106:107], 0
	v_mov_b64_e32 v[116:117], 0
	v_mov_b64_e32 v[118:119], 0
	v_mov_b64_e32 v[120:121], 0
	v_mov_b64_e32 v[122:123], 0
	v_mov_b64_e32 v[76:77], 0
	v_mov_b64_e32 v[78:79], 0
	v_mov_b64_e32 v[80:81], 0
	v_mov_b64_e32 v[82:83], 0
	v_mov_b64_e32 v[92:93], 0
	v_mov_b64_e32 v[94:95], 0
	v_mov_b64_e32 v[96:97], 0
	v_mov_b64_e32 v[98:99], 0
	v_mov_b64_e32 v[108:109], 0
	v_mov_b64_e32 v[110:111], 0
	v_mov_b64_e32 v[112:113], 0
	v_mov_b64_e32 v[114:115], 0
	v_mov_b64_e32 v[124:125], 0
	v_mov_b64_e32 v[126:127], 0
	v_mov_b64_e32 v[128:129], 0
	v_mov_b64_e32 v[130:131], 0
	v_readfirstlane_b32 s101, v172
	s_nop 3
	s_cmp_ge_u32 s101, 0x100
	s_cbranch_scc1 .Lprio_hi_563
	s_setprio 1
	s_branch .Lprio_done_563

; template <class Epi, class Sched, bool ALIGN_EPI = false, bool SP2 = false>
; __device__ __forceinline__ void gemm_phase(PG8_LAS unsigned char* lds, const Gemm g, const Sched& S, const Epi& E) {
;     ...
;         const bool has_next = S.next(ui + 1, nxt);
;         const char* nA = has_next ? (const char*)g.A + (size_t)nxt.pm * tstep : cA; const char* nB = has_next ? (const char*)g.Bt + (size_t)nxt.pn * tstep : cB;
;         for (int t = 0; t < nt; t += 2) {
;             const bool last = (t == nt - 2);
;             const char* a1 = cA + (size_t)(t + 1) * kstep;
;             const char* a2 = last ? nA : cA + (size_t)(t + 2) * kstep; const char* b2 = last ? nB : cB + (size_t)(t + 2) * kstep;
;             const char* a3 = a2 + kstep; const char* b3 = b2 + kstep;
;     ...
; #pragma unroll
;         for (int a = 0; a < 2; ++a)
; #pragma unroll
;             for (int b = 0; b < 2; ++b)
; #pragma unroll
;                 for (int m = 0; m < 4; ++m)
; #pragma unroll
;                     for (int n = 0; n < 2; ++n) acc[a][b][m][n] = (f32x4){0.f, 0.f, 0.f, 0.f};
;         cur = nxt; cA = nA; cB = nB; ++ui;
.LBB0_659:
	s_ashr_i32 s65, s64, 31
	s_lshl_b64 s[16:17], s[64:65], 20
	s_add_u32 s66, s19, s16
	s_addc_u32 s67, s20, s17
	s_and_b64 s[16:17], s[40:41], exec
	s_cselect_b32 s23, s67, s15
	s_cselect_b32 s24, s66, s14
	s_ashr_i32 s63, s62, 31
	s_lshl_b64 s[16:17], s[62:63], 20
	s_add_u32 s68, s26, s16
	s_addc_u32 s69, s27, s17
	s_and_b64 s[16:17], s[40:41], exec
	s_cselect_b32 s25, s69, s1
	s_cselect_b32 s42, s68, s0
	s_add_u32 s43, s0, 0x100
	s_addc_u32 s44, s1, 0
	s_add_u32 s0, s14, 0x80080
	v_mov_b32_e32 v4, 0
	s_addc_u32 s1, s15, 0
	s_mov_b32 s45, -2
	v_mov_b32_e32 v5, v4
	v_mov_b64_e32 v[6:7], 0
	v_mov_b64_e32 v[8:9], 0
	v_mov_b64_e32 v[10:11], 0
	v_mov_b64_e32 v[12:13], 0
	v_mov_b64_e32 v[14:15], 0
	v_mov_b64_e32 v[16:17], 0
	v_mov_b64_e32 v[18:19], 0
	v_mov_b64_e32 v[20:21], 0
	v_mov_b64_e32 v[22:23], 0
	v_mov_b64_e32 v[24:25], 0
	v_mov_b64_e32 v[26:27], 0
	s_waitcnt vmcnt(0)
	v_mov_b64_e32 v[28:29], 0
	v_mov_b64_e32 v[30:31], 0
	v_mov_b64_e32 v[32:33], 0
	v_mov_b64_e32 v[34:35], 0
	v_mov_b64_e32 v[88:89], 0
	v_mov_b64_e32 v[90:91], 0
	v_mov_b64_e32 v[92:93], 0
	v_mov_b64_e32 v[94:95], 0
	v_mov_b64_e32 v[52:53], 0
	v_mov_b64_e32 v[54:55], 0
	v_mov_b64_e32 v[56:57], 0
	v_mov_b64_e32 v[58:59], 0
	v_mov_b64_e32 v[60:61], 0
	v_mov_b64_e32 v[62:63], 0
	v_mov_b64_e32 v[64:65], 0
	v_mov_b64_e32 v[66:67], 0
	v_mov_b64_e32 v[68:69], 0
	v_mov_b64_e32 v[70:71], 0
	v_mov_b64_e32 v[72:73], 0
	v_mov_b64_e32 v[74:75], 0
	v_mov_b64_e32 v[100:101], 0
	v_mov_b64_e32 v[102:103], 0
	v_mov_b64_e32 v[104:105], 0
	v_mov_b64_e32 v[106:107], 0
	v_mov_b64_e32 v[108:109], 0
	v_mov_b64_e32 v[110:111], 0
	v_mov_b64_e32 v[112:113], 0
	v_mov_b64_e32 v[114:115], 0
	v_mov_b64_e32 v[116:117], 0
	v_mov_b64_e32 v[118:119], 0
	v_mov_b64_e32 v[120:121], 0
	v_mov_b64_e32 v[122:123], 0
	v_mov_b64_e32 v[140:141], 0
	v_mov_b64_e32 v[142:143], 0
	v_mov_b64_e32 v[144:145], 0
	v_mov_b64_e32 v[146:147], 0
	v_mov_b64_e32 v[156:157], 0
	v_mov_b64_e32 v[158:159], 0
	v_mov_b64_e32 v[160:161], 0
	v_mov_b64_e32 v[162:163], 0
	v_mov_b64_e32 v[124:125], 0
	v_mov_b64_e32 v[126:127], 0
	v_mov_b64_e32 v[128:129], 0
	v_mov_b64_e32 v[130:131], 0
	v_mov_b64_e32 v[132:133], 0
	v_mov_b64_e32 v[134:135], 0
	v_mov_b64_e32 v[136:137], 0
	v_mov_b64_e32 v[138:139], 0
	v_mov_b64_e32 v[148:149], 0
	v_mov_b64_e32 v[150:151], 0
	v_mov_b64_e32 v[152:153], 0
	v_mov_b64_e32 v[154:155], 0
	v_readfirstlane_b32 s101, v172
	s_nop 3
	s_cmp_ge_u32 s101, 0x100
	s_cbranch_scc1 .Lprio_hi_660
	s_setprio 1
	s_branch .Lprio_done_660

; template <class Epi, class Sched, bool ALIGN_EPI = false, bool SP2 = false>
; __device__ __forceinline__ void gemm_phase(PG8_LAS unsigned char* lds, const Gemm g, const Sched& S, const Epi& E) {
;     ...
; #pragma unroll
;         for (int a = 0; a < 2; ++a)
; #pragma unroll
;             for (int b = 0; b < 2; ++b)
; #pragma unroll
;                 for (int m = 0; m < 4; ++m)
; #pragma unroll
;                     for (int n = 0; n < 2; ++n) acc[a][b][m][n] = (f32x4){0.f, 0.f, 0.f, 0.f};
;         cur = nxt; cA = nA; cB = nB; ++ui;
.LBB0_821:
	s_add_u32 s23, s14, 0x100
	v_mov_b32_e32 v4, 0
	s_addc_u32 s24, s15, 0
	s_mov_b32 s25, -2
	s_waitcnt lgkmcnt(0)
	v_mov_b32_e32 v5, v4
	v_mov_b64_e32 v[6:7], 0
	v_mov_b64_e32 v[8:9], 0
	v_mov_b64_e32 v[10:11], 0
	v_mov_b64_e32 v[20:21], 0
	v_mov_b64_e32 v[22:23], 0
	v_mov_b64_e32 v[24:25], 0
	v_mov_b64_e32 v[26:27], 0
	s_waitcnt vmcnt(0)
	v_mov_b64_e32 v[36:37], 0
	v_mov_b64_e32 v[38:39], 0
	v_mov_b64_e32 v[40:41], 0
	v_mov_b64_e32 v[42:43], 0
	v_mov_b64_e32 v[52:53], 0
	v_mov_b64_e32 v[54:55], 0
	v_mov_b64_e32 v[56:57], 0
	v_mov_b64_e32 v[58:59], 0
	v_mov_b64_e32 v[12:13], 0
	v_mov_b64_e32 v[14:15], 0
	v_mov_b64_e32 v[16:17], 0
	v_mov_b64_e32 v[18:19], 0
	v_mov_b64_e32 v[28:29], 0
	v_mov_b64_e32 v[30:31], 0
	v_mov_b64_e32 v[32:33], 0
	v_mov_b64_e32 v[34:35], 0
	v_mov_b64_e32 v[44:45], 0
	v_mov_b64_e32 v[46:47], 0
	v_mov_b64_e32 v[48:49], 0
	v_mov_b64_e32 v[50:51], 0
	v_mov_b64_e32 v[60:61], 0
	v_mov_b64_e32 v[62:63], 0
	v_mov_b64_e32 v[64:65], 0
	v_mov_b64_e32 v[66:67], 0
	v_mov_b64_e32 v[68:69], 0
	v_mov_b64_e32 v[70:71], 0
	v_mov_b64_e32 v[72:73], 0
	v_mov_b64_e32 v[74:75], 0
	v_mov_b64_e32 v[84:85], 0
	v_mov_b64_e32 v[86:87], 0
	v_mov_b64_e32 v[88:89], 0
	v_mov_b64_e32 v[90:91], 0
	v_mov_b64_e32 v[100:101], 0
	v_mov_b64_e32 v[102:103], 0
	v_mov_b64_e32 v[104:105], 0
	v_mov_b64_e32 v[106:107], 0
	v_mov_b64_e32 v[124:125], 0
	v_mov_b64_e32 v[126:127], 0
	v_mov_b64_e32 v[128:129], 0
	v_mov_b64_e32 v[130:131], 0
	v_mov_b64_e32 v[76:77], 0
	v_mov_b64_e32 v[78:79], 0
	v_mov_b64_e32 v[80:81], 0
	v_mov_b64_e32 v[82:83], 0
	v_mov_b64_e32 v[92:93], 0
	v_mov_b64_e32 v[94:95], 0
	v_mov_b64_e32 v[96:97], 0
	v_mov_b64_e32 v[98:99], 0
	v_mov_b64_e32 v[108:109], 0
	v_mov_b64_e32 v[110:111], 0
	v_mov_b64_e32 v[112:113], 0
	v_mov_b64_e32 v[114:115], 0
	v_mov_b64_e32 v[132:133], 0
	v_mov_b64_e32 v[134:135], 0
	v_mov_b64_e32 v[136:137], 0
	v_mov_b64_e32 v[138:139], 0
	v_readfirstlane_b32 s101, v172
	s_nop 3
	s_cmp_ge_u32 s101, 0x100
	s_cbranch_scc1 .Lprio_hi_822
	s_setprio 1
	s_branch .Lprio_done_822
